# out-proj residual epilogue: next block's x loads retargeted to free v168-175 and issued before the previous block's store (vmcnt 2/1), so waits no longer cover the store ack
# baseline (speedup 1.0000x reference)
; __device__ __forceinline__ unsigned cvt_pk_bf16(float lo, float hi) { unsigned r; asm volatile("v_cvt_pk_bf16_f32 %0, %1, %2" : "=v"(r) : "v"(lo), "v"(hi)); return r; }
;     __device__ __forceinline__ void operator()(const f32x4 (&acc)[2][2][4][2], const Unit& u, int wr, int wc, int fr, int fq) const {
;     ...
;         if (F32BASE) {
; #pragma unroll
;             for (int ai = 0; ai < 2; ++ai)
; #pragma unroll
;                 for (int m = 0; m < 4; ++m) { const size_t roff = (size_t)(row0 + ai * HALF + m * 16) * ldc + col0;
; #pragma unroll
;                     for (int bj = 0; bj < 2; ++bj) { const size_t off = roff + bj * HALF; const f32x4 v0 = acc[ai][bj][m][0] + *(const f32x4*)(basef + off), v1 = acc[ai][bj][m][1] + *(const f32x4*)(basef + off + 4);
;                         u32x4 w; w.x = cvt_pk_bf16(v0[0], v0[1]); w.y = cvt_pk_bf16(v0[2], v0[3]); w.z = cvt_pk_bf16(v1[0], v1[1]); w.w = cvt_pk_bf16(v1[2], v1[3]);
;                         *(u32x4*)(outb + off) = w; }
;                     if (m & 1) asm volatile("" ::: "memory"); }
.LBB0_248:
	v_lshl_add_u32 v148, s68, 8, v150
	v_lshl_or_b32 v146, s24, 8, v152
	v_ashrrev_i32_e32 v149, 31, v148
	v_ashrrev_i32_e32 v147, 31, v146
	v_lshlrev_b64 v[144:145], 11, v[148:149]
	v_lshl_add_u64 v[144:145], v[144:145], 0, v[146:147]
	v_lshl_add_u64 v[164:165], v[144:145], 2, s[36:37]
	global_load_dwordx4 v[156:159], v[164:165], off
	global_load_dwordx4 v[160:163], v[164:165], off offset:16
	v_lshl_add_u64 v[166:167], v[144:145], 1, s[52:53]
	s_mov_b64 s[24:25], 0x40000
	s_andn2_b64 vcc, exec, s[4:5]
	s_mov_b64 s[4:5], -1
	s_waitcnt vmcnt(0)
	v_pk_add_f32 v[124:125], v[124:125], v[156:157]
	v_pk_add_f32 v[156:157], v[122:123], v[162:163]
	v_pk_add_f32 v[122:123], v[120:121], v[160:161]
	v_pk_add_f32 v[126:127], v[126:127], v[158:159]
	v_cvt_pk_bf16_f32 v120, v124, v125
	s_nop 0
	v_cvt_pk_bf16_f32 v121, v126, v127
	v_cvt_pk_bf16_f32 v122, v122, v123
	v_cvt_pk_bf16_f32 v123, v156, v157
	global_load_dwordx4 v[168:171], v[164:165], off offset:512
	s_nop 0
	global_load_dwordx4 v[172:175], v[164:165], off offset:528
	global_store_dwordx4 v[166:167], v[120:123], off
	v_or_b32_e32 v156, 16, v148
	v_ashrrev_i32_e32 v157, 31, v156
	v_lshlrev_b64 v[156:157], 11, v[156:157]
	v_lshl_add_u64 v[156:157], v[156:157], 0, v[146:147]
	v_lshl_add_u64 v[158:159], v[156:157], 2, s[36:37]
	s_waitcnt vmcnt(2)
	v_pk_add_f32 v[116:117], v[116:117], v[168:169]
	s_waitcnt vmcnt(1)
	v_pk_add_f32 v[120:121], v[114:115], v[174:175]
	v_pk_add_f32 v[114:115], v[112:113], v[172:173]
	v_pk_add_f32 v[118:119], v[118:119], v[170:171]
	v_cvt_pk_bf16_f32 v112, v116, v117
	s_nop 0
	v_cvt_pk_bf16_f32 v113, v118, v119
	v_cvt_pk_bf16_f32 v114, v114, v115
	v_cvt_pk_bf16_f32 v115, v120, v121
	global_load_dwordx4 v[168:171], v[158:159], off
	s_nop 0
	global_load_dwordx4 v[172:175], v[158:159], off offset:16
	global_store_dwordx4 v[166:167], v[112:115], off offset:256
	v_lshl_add_u64 v[120:121], v[156:157], 1, s[52:53]
	s_waitcnt vmcnt(2)
	v_pk_add_f32 v[108:109], v[108:109], v[168:169]
	s_waitcnt vmcnt(1)
	v_pk_add_f32 v[112:113], v[106:107], v[174:175]
	v_pk_add_f32 v[106:107], v[104:105], v[172:173]
	v_pk_add_f32 v[110:111], v[110:111], v[170:171]
	v_cvt_pk_bf16_f32 v104, v108, v109
	s_nop 0
	v_cvt_pk_bf16_f32 v105, v110, v111
	v_cvt_pk_bf16_f32 v106, v106, v107
	v_cvt_pk_bf16_f32 v107, v112, v113
	global_load_dwordx4 v[168:171], v[158:159], off offset:512
	s_nop 0
	global_load_dwordx4 v[172:175], v[158:159], off offset:528
	global_store_dwordx4 v[120:121], v[104:107], off
	v_or_b32_e32 v112, 32, v148
	v_ashrrev_i32_e32 v113, 31, v112
	v_lshlrev_b64 v[112:113], 11, v[112:113]
	v_lshl_add_u64 v[112:113], v[112:113], 0, v[146:147]
	v_lshl_add_u64 v[114:115], v[112:113], 2, s[36:37]
	s_waitcnt vmcnt(2)
	v_pk_add_f32 v[100:101], v[100:101], v[168:169]
	s_waitcnt vmcnt(1)
	v_pk_add_f32 v[104:105], v[98:99], v[174:175]
	v_pk_add_f32 v[98:99], v[96:97], v[172:173]
	v_pk_add_f32 v[102:103], v[102:103], v[170:171]
	v_cvt_pk_bf16_f32 v96, v100, v101
	s_nop 0
	v_cvt_pk_bf16_f32 v97, v102, v103
	v_cvt_pk_bf16_f32 v98, v98, v99
	v_cvt_pk_bf16_f32 v99, v104, v105
	global_load_dwordx4 v[168:171], v[114:115], off
	global_load_dwordx4 v[172:175], v[114:115], off offset:16
	global_store_dwordx4 v[120:121], v[96:99], off offset:256
	v_lshl_add_u64 v[104:105], v[112:113], 1, s[52:53]
	s_waitcnt vmcnt(2)
	v_pk_add_f32 v[92:93], v[92:93], v[168:169]
	s_waitcnt vmcnt(1)
	v_pk_add_f32 v[96:97], v[90:91], v[174:175]
	v_pk_add_f32 v[90:91], v[88:89], v[172:173]
	v_pk_add_f32 v[94:95], v[94:95], v[170:171]
	v_cvt_pk_bf16_f32 v88, v92, v93
	s_nop 0
	v_cvt_pk_bf16_f32 v89, v94, v95
	v_cvt_pk_bf16_f32 v90, v90, v91
	v_cvt_pk_bf16_f32 v91, v96, v97
	global_load_dwordx4 v[168:171], v[114:115], off offset:512
	s_nop 0
	global_load_dwordx4 v[172:175], v[114:115], off offset:528
	global_store_dwordx4 v[104:105], v[88:91], off
	v_or_b32_e32 v96, 48, v148
	v_ashrrev_i32_e32 v97, 31, v96
	v_lshlrev_b64 v[96:97], 11, v[96:97]
	v_lshl_add_u64 v[96:97], v[96:97], 0, v[146:147]
	v_lshl_add_u64 v[98:99], v[96:97], 2, s[36:37]
	s_waitcnt vmcnt(2)
	v_pk_add_f32 v[84:85], v[84:85], v[168:169]
	s_waitcnt vmcnt(1)
	v_pk_add_f32 v[88:89], v[82:83], v[174:175]
	v_pk_add_f32 v[82:83], v[80:81], v[172:173]
	v_pk_add_f32 v[86:87], v[86:87], v[170:171]
	v_cvt_pk_bf16_f32 v80, v84, v85
	s_nop 0
	v_cvt_pk_bf16_f32 v81, v86, v87
	v_cvt_pk_bf16_f32 v82, v82, v83
	v_cvt_pk_bf16_f32 v83, v88, v89
	global_load_dwordx4 v[168:171], v[98:99], off
	s_nop 0
	global_load_dwordx4 v[172:175], v[98:99], off offset:16
	global_store_dwordx4 v[104:105], v[80:83], off offset:256
	v_lshl_add_u64 v[88:89], v[96:97], 1, s[52:53]
	s_waitcnt vmcnt(2)
	v_pk_add_f32 v[76:77], v[76:77], v[168:169]
	s_waitcnt vmcnt(1)
	v_pk_add_f32 v[80:81], v[74:75], v[174:175]
	v_pk_add_f32 v[74:75], v[72:73], v[172:173]
	v_pk_add_f32 v[78:79], v[78:79], v[170:171]
	v_cvt_pk_bf16_f32 v72, v76, v77
	s_nop 0
	v_cvt_pk_bf16_f32 v73, v78, v79
	v_cvt_pk_bf16_f32 v74, v74, v75
	v_cvt_pk_bf16_f32 v75, v80, v81
	global_load_dwordx4 v[168:171], v[98:99], off offset:512
	s_nop 0
	global_load_dwordx4 v[172:175], v[98:99], off offset:528
	global_store_dwordx4 v[88:89], v[72:75], off
	v_lshl_add_u64 v[80:81], v[144:145], 0, s[24:25]
	v_lshl_add_u64 v[82:83], v[80:81], 2, s[36:37]
	s_mov_b64 s[24:25], 0x48000
	s_waitcnt vmcnt(2)
; __device__ __forceinline__ unsigned cvt_pk_bf16(float lo, float hi) { unsigned r; asm volatile("v_cvt_pk_bf16_f32 %0, %1, %2" : "=v"(r) : "v"(lo), "v"(hi)); return r; }
;     __device__ __forceinline__ void operator()(const f32x4 (&acc)[2][2][4][2], const Unit& u, int wr, int wc, int fr, int fq) const {
;     ...
;                 for (int m = 0; m < 4; ++m) { const size_t roff = (size_t)(row0 + ai * HALF + m * 16) * ldc + col0;
; #pragma unroll
;                     for (int bj = 0; bj < 2; ++bj) { const size_t off = roff + bj * HALF; const f32x4 v0 = acc[ai][bj][m][0] + *(const f32x4*)(basef + off), v1 = acc[ai][bj][m][1] + *(const f32x4*)(basef + off + 4);
;                         u32x4 w; w.x = cvt_pk_bf16(v0[0], v0[1]); w.y = cvt_pk_bf16(v0[2], v0[3]); w.z = cvt_pk_bf16(v1[0], v1[1]); w.w = cvt_pk_bf16(v1[2], v1[3]);
;                         *(u32x4*)(outb + off) = w; }
;                     if (m & 1) asm volatile("" ::: "memory"); }
	v_pk_add_f32 v[68:69], v[68:69], v[168:169]
	s_waitcnt vmcnt(1)
	v_pk_add_f32 v[72:73], v[66:67], v[174:175]
	v_pk_add_f32 v[66:67], v[64:65], v[172:173]
	v_pk_add_f32 v[70:71], v[70:71], v[170:171]
	v_cvt_pk_bf16_f32 v64, v68, v69
	s_nop 0
	v_cvt_pk_bf16_f32 v65, v70, v71
	v_cvt_pk_bf16_f32 v66, v66, v67
	v_cvt_pk_bf16_f32 v67, v72, v73
	global_load_dwordx4 v[168:171], v[82:83], off
	global_load_dwordx4 v[172:175], v[82:83], off offset:16
	global_store_dwordx4 v[88:89], v[64:67], off offset:256
	v_lshl_add_u64 v[72:73], v[80:81], 1, s[52:53]
	s_waitcnt vmcnt(2)
	v_pk_add_f32 v[60:61], v[60:61], v[168:169]
	s_waitcnt vmcnt(1)
	v_pk_add_f32 v[64:65], v[58:59], v[174:175]
	v_pk_add_f32 v[58:59], v[56:57], v[172:173]
	v_pk_add_f32 v[62:63], v[62:63], v[170:171]
	v_cvt_pk_bf16_f32 v56, v60, v61
	s_nop 0
	v_cvt_pk_bf16_f32 v57, v62, v63
	v_cvt_pk_bf16_f32 v58, v58, v59
	v_cvt_pk_bf16_f32 v59, v64, v65
	global_load_dwordx4 v[168:171], v[82:83], off offset:512
	s_nop 0
	global_load_dwordx4 v[172:175], v[82:83], off offset:528
	global_store_dwordx4 v[72:73], v[56:59], off
	v_lshl_add_u64 v[64:65], v[144:145], 0, s[24:25]
	v_lshl_add_u64 v[66:67], v[64:65], 2, s[36:37]
	s_waitcnt vmcnt(2)
	v_pk_add_f32 v[52:53], v[52:53], v[168:169]
	s_waitcnt vmcnt(1)
	v_pk_add_f32 v[56:57], v[50:51], v[174:175]
	v_pk_add_f32 v[50:51], v[48:49], v[172:173]
	v_pk_add_f32 v[54:55], v[54:55], v[170:171]
	v_cvt_pk_bf16_f32 v48, v52, v53
	s_nop 0
	v_cvt_pk_bf16_f32 v49, v54, v55
	v_cvt_pk_bf16_f32 v50, v50, v51
	v_cvt_pk_bf16_f32 v51, v56, v57
	global_load_dwordx4 v[168:171], v[66:67], off
	s_nop 0
	global_load_dwordx4 v[172:175], v[66:67], off offset:16
	global_store_dwordx4 v[72:73], v[48:51], off offset:256
	v_lshl_add_u64 v[56:57], v[64:65], 1, s[52:53]
	s_waitcnt vmcnt(2)
	v_pk_add_f32 v[44:45], v[44:45], v[168:169]
	s_waitcnt vmcnt(1)
	v_pk_add_f32 v[48:49], v[42:43], v[174:175]
	v_pk_add_f32 v[42:43], v[40:41], v[172:173]
	v_pk_add_f32 v[46:47], v[46:47], v[170:171]
	v_cvt_pk_bf16_f32 v40, v44, v45
	s_nop 0
	v_cvt_pk_bf16_f32 v41, v46, v47
	v_cvt_pk_bf16_f32 v42, v42, v43
	v_cvt_pk_bf16_f32 v43, v48, v49
	global_load_dwordx4 v[168:171], v[66:67], off offset:512
	s_nop 0
	global_load_dwordx4 v[172:175], v[66:67], off offset:528
	global_store_dwordx4 v[56:57], v[40:43], off
	v_lshl_add_u64 v[48:49], v[144:145], 0, s[44:45]
	v_lshl_add_u64 v[50:51], v[48:49], 2, s[36:37]
	s_waitcnt vmcnt(2)
	v_pk_add_f32 v[36:37], v[36:37], v[168:169]
	s_waitcnt vmcnt(1)
	v_pk_add_f32 v[40:41], v[34:35], v[174:175]
	v_pk_add_f32 v[34:35], v[32:33], v[172:173]
	v_pk_add_f32 v[38:39], v[38:39], v[170:171]
	v_cvt_pk_bf16_f32 v32, v36, v37
	s_nop 0
	v_cvt_pk_bf16_f32 v33, v38, v39
	v_cvt_pk_bf16_f32 v34, v34, v35
	v_cvt_pk_bf16_f32 v35, v40, v41
	global_load_dwordx4 v[168:171], v[50:51], off
	global_load_dwordx4 v[172:175], v[50:51], off offset:16
	global_store_dwordx4 v[56:57], v[32:35], off offset:256
	v_lshl_add_u64 v[40:41], v[48:49], 1, s[52:53]
	s_waitcnt vmcnt(2)
	v_pk_add_f32 v[28:29], v[28:29], v[168:169]
	s_waitcnt vmcnt(1)
	v_pk_add_f32 v[32:33], v[26:27], v[174:175]
	v_pk_add_f32 v[26:27], v[24:25], v[172:173]
	v_pk_add_f32 v[30:31], v[30:31], v[170:171]
	v_cvt_pk_bf16_f32 v24, v28, v29
	s_nop 0
	v_cvt_pk_bf16_f32 v25, v30, v31
	v_cvt_pk_bf16_f32 v26, v26, v27
	v_cvt_pk_bf16_f32 v27, v32, v33
	global_load_dwordx4 v[168:171], v[50:51], off offset:512
	s_nop 0
	global_load_dwordx4 v[172:175], v[50:51], off offset:528
	global_store_dwordx4 v[40:41], v[24:27], off
	v_lshl_add_u64 v[32:33], v[144:145], 0, s[48:49]
	v_lshl_add_u64 v[34:35], v[32:33], 2, s[36:37]
	s_waitcnt vmcnt(2)
	v_pk_add_f32 v[20:21], v[20:21], v[168:169]
	s_waitcnt vmcnt(1)
	v_pk_add_f32 v[24:25], v[18:19], v[174:175]
	v_pk_add_f32 v[18:19], v[16:17], v[172:173]
	v_pk_add_f32 v[22:23], v[22:23], v[170:171]
	v_cvt_pk_bf16_f32 v16, v20, v21
	s_nop 0
	v_cvt_pk_bf16_f32 v17, v22, v23
	v_cvt_pk_bf16_f32 v18, v18, v19
	v_cvt_pk_bf16_f32 v19, v24, v25
	global_load_dwordx4 v[168:171], v[34:35], off
	s_nop 0
	global_load_dwordx4 v[172:175], v[34:35], off offset:16
	global_store_dwordx4 v[40:41], v[16:19], off offset:256
	v_lshl_add_u64 v[24:25], v[32:33], 1, s[52:53]
	s_waitcnt vmcnt(2)
	v_pk_add_f32 v[12:13], v[12:13], v[168:169]
	s_waitcnt vmcnt(1)
	v_pk_add_f32 v[16:17], v[10:11], v[174:175]
	v_pk_add_f32 v[10:11], v[8:9], v[172:173]
	v_pk_add_f32 v[14:15], v[14:15], v[170:171]
	v_cvt_pk_bf16_f32 v8, v12, v13
	s_nop 0
	v_cvt_pk_bf16_f32 v9, v14, v15
	v_cvt_pk_bf16_f32 v10, v10, v11
	v_cvt_pk_bf16_f32 v11, v16, v17
	global_load_dwordx4 v[168:171], v[34:35], off offset:512
	s_nop 0
	global_load_dwordx4 v[172:175], v[34:35], off offset:528
	global_store_dwordx4 v[24:25], v[8:11], off
	s_waitcnt vmcnt(2)
	v_pk_add_f32 v[4:5], v[4:5], v[168:169]
	s_waitcnt vmcnt(1)
	v_pk_add_f32 v[8:9], v[2:3], v[174:175]
	v_pk_add_f32 v[2:3], v[0:1], v[172:173]
	v_pk_add_f32 v[6:7], v[6:7], v[170:171]
	v_cvt_pk_bf16_f32 v0, v4, v5
	s_nop 0
	v_cvt_pk_bf16_f32 v1, v6, v7
	v_cvt_pk_bf16_f32 v2, v2, v3
	v_cvt_pk_bf16_f32 v3, v8, v9
	global_store_dwordx4 v[24:25], v[0:3], off offset:256
	s_cbranch_vccnz .LBB0_237
	s_andn2_b64 vcc, exec, s[6:7]
	s_cbranch_vccnz .LBB0_236
	s_barrier
	s_branch .LBB0_236
